# a9 + ret_scan load de-serialisation: 32 chunk loads in flight per pass (was 8 with a wait per group), same arithmetic order
# speedup vs baseline: 1.0066x; 1.0035x over previous
.LBB0_807:
	v_cmp_gt_u32_e32 vcc, s3, v4
	v_lshrrev_b32_e32 v0, 11, v4
	v_and_b32_e32 v0, 28, v0
	v_cndmask_b32_e32 v3, v5, v6, vcc
	v_cndmask_b32_e32 v2, v7, v8, vcc
	v_lshl_add_u64 v[2:3], v[2:3], 0, v[0:1]
	global_load_dword v10, v[2:3], off
	v_bfe_u32 v0, v4, 13, 4
	v_ashrrev_i32_e32 v2, 13, v4
	v_and_b32_e32 v3, 0x1fff, v4
	v_and_or_b32 v0, v2, s23, v0
	v_lshlrev_b32_e32 v2, 6, v0
	v_lshlrev_b32_e32 v0, 1, v3
	s_waitcnt vmcnt(0)
	v_mul_f32_e32 v3, 0x3fb8aa3b, v10
	v_fma_f32 v11, v10, s8, -v3
	v_rndne_f32_e32 v12, v3
	v_fmac_f32_e32 v11, 0x32a5705f, v10
	v_sub_f32_e32 v3, v3, v12
	v_add_f32_e32 v3, v3, v11
	v_cvt_i32_f32_e32 v12, v12
	v_exp_f32_e32 v11, v3
	v_cmp_ngt_f32_e64 s[0:1], s9, v10
	v_ashrrev_i32_e32 v3, 31, v2
	v_lshlrev_b64 v[2:3], 14, v[2:3]
	v_ldexp_f32 v11, v11, v12
	v_cndmask_b32_e64 v11, 0, v11, s[0:1]
	v_cmp_nlt_f32_e64 s[0:1], s22, v10
	v_lshl_add_u64 v[2:3], s[18:19], 0, v[2:3]
	v_lshl_add_u64 v[2:3], v[2:3], 0, v[0:1]
	v_cndmask_b32_e64 v10, v9, v11, s[0:1]
	v_mul_f32_e32 v10, 0xbfb8aa3b, v10
	v_mul_f32_e32 v10, 0x43000000, v10
	v_exp_f32_e32 v10, v10
	s_and_b64 s[38:39], vcc, exec
	s_cmp_lg_u64 s[38:39], 0
	s_mov_b32 s44, 0xffffc000
	s_cselect_b32 s40, 0x4000, s44
	s_cselect_b32 s41, 0, -1
	s_cselect_b32 s42, 0, 0xfc000
	s_mov_b32 s43, 0
	v_lshl_add_u64 v[12:13], v[2:3], 0, s[42:43]
	v_mov_b32_e32 v0, 0
	v_mov_b32_e32 v14, v12
	v_mov_b32_e32 v15, v13
	global_load_ushort v40, v[12:13], off
	v_lshl_add_u64 v[12:13], v[12:13], 0, s[40:41]
	global_load_ushort v41, v[12:13], off
	v_lshl_add_u64 v[12:13], v[12:13], 0, s[40:41]
	global_load_ushort v42, v[12:13], off
	v_lshl_add_u64 v[12:13], v[12:13], 0, s[40:41]
	global_load_ushort v43, v[12:13], off
	v_lshl_add_u64 v[12:13], v[12:13], 0, s[40:41]
	global_load_ushort v44, v[12:13], off
	v_lshl_add_u64 v[12:13], v[12:13], 0, s[40:41]
	global_load_ushort v45, v[12:13], off
	v_lshl_add_u64 v[12:13], v[12:13], 0, s[40:41]
	global_load_ushort v46, v[12:13], off
	v_lshl_add_u64 v[12:13], v[12:13], 0, s[40:41]
	global_load_ushort v47, v[12:13], off
	v_lshl_add_u64 v[12:13], v[12:13], 0, s[40:41]
	global_load_ushort v48, v[12:13], off
	v_lshl_add_u64 v[12:13], v[12:13], 0, s[40:41]
	global_load_ushort v49, v[12:13], off
	v_lshl_add_u64 v[12:13], v[12:13], 0, s[40:41]
	global_load_ushort v50, v[12:13], off
	v_lshl_add_u64 v[12:13], v[12:13], 0, s[40:41]
	global_load_ushort v51, v[12:13], off
	v_lshl_add_u64 v[12:13], v[12:13], 0, s[40:41]
	global_load_ushort v52, v[12:13], off
	v_lshl_add_u64 v[12:13], v[12:13], 0, s[40:41]
	global_load_ushort v53, v[12:13], off
	v_lshl_add_u64 v[12:13], v[12:13], 0, s[40:41]
	global_load_ushort v54, v[12:13], off
	v_lshl_add_u64 v[12:13], v[12:13], 0, s[40:41]
	global_load_ushort v55, v[12:13], off
	v_lshl_add_u64 v[12:13], v[12:13], 0, s[40:41]
	global_load_ushort v56, v[12:13], off
	v_lshl_add_u64 v[12:13], v[12:13], 0, s[40:41]
	global_load_ushort v57, v[12:13], off
	v_lshl_add_u64 v[12:13], v[12:13], 0, s[40:41]
	global_load_ushort v58, v[12:13], off
	v_lshl_add_u64 v[12:13], v[12:13], 0, s[40:41]
	global_load_ushort v59, v[12:13], off
	v_lshl_add_u64 v[12:13], v[12:13], 0, s[40:41]
	global_load_ushort v60, v[12:13], off
	v_lshl_add_u64 v[12:13], v[12:13], 0, s[40:41]
	global_load_ushort v61, v[12:13], off
	v_lshl_add_u64 v[12:13], v[12:13], 0, s[40:41]
	global_load_ushort v62, v[12:13], off
	v_lshl_add_u64 v[12:13], v[12:13], 0, s[40:41]
	global_load_ushort v63, v[12:13], off
	v_lshl_add_u64 v[12:13], v[12:13], 0, s[40:41]
	global_load_ushort v64, v[12:13], off
	v_lshl_add_u64 v[12:13], v[12:13], 0, s[40:41]
	global_load_ushort v65, v[12:13], off
	v_lshl_add_u64 v[12:13], v[12:13], 0, s[40:41]
	global_load_ushort v66, v[12:13], off
	v_lshl_add_u64 v[12:13], v[12:13], 0, s[40:41]
	global_load_ushort v67, v[12:13], off
	v_lshl_add_u64 v[12:13], v[12:13], 0, s[40:41]
	global_load_ushort v68, v[12:13], off
	v_lshl_add_u64 v[12:13], v[12:13], 0, s[40:41]
	global_load_ushort v69, v[12:13], off
	v_lshl_add_u64 v[12:13], v[12:13], 0, s[40:41]
	global_load_ushort v70, v[12:13], off
	v_lshl_add_u64 v[12:13], v[12:13], 0, s[40:41]
	global_load_ushort v71, v[12:13], off
	v_lshl_add_u64 v[12:13], v[12:13], 0, s[40:41]
	global_load_ushort v72, v[12:13], off
	v_lshl_add_u64 v[12:13], v[12:13], 0, s[40:41]
	v_cvt_pk_bf16_f32 v16, v0, v0
	s_waitcnt vmcnt(32)
	global_store_short v[14:15], v16, off
	v_lshl_add_u64 v[14:15], v[14:15], 0, s[40:41]
	v_lshlrev_b32_e32 v40, 16, v40
	v_fmac_f32_e32 v40, v10, v0
	global_load_ushort v73, v[12:13], off
	v_lshl_add_u64 v[12:13], v[12:13], 0, s[40:41]
	v_cvt_pk_bf16_f32 v16, v40, v40
	s_waitcnt vmcnt(33)
	global_store_short v[14:15], v16, off
	v_lshl_add_u64 v[14:15], v[14:15], 0, s[40:41]
	v_lshlrev_b32_e32 v41, 16, v41
	v_fmac_f32_e32 v41, v10, v40
	global_load_ushort v74, v[12:13], off
	v_lshl_add_u64 v[12:13], v[12:13], 0, s[40:41]
	v_cvt_pk_bf16_f32 v16, v41, v41
	s_waitcnt vmcnt(34)
	global_store_short v[14:15], v16, off
	v_lshl_add_u64 v[14:15], v[14:15], 0, s[40:41]
	v_lshlrev_b32_e32 v42, 16, v42
	v_fmac_f32_e32 v42, v10, v41
	global_load_ushort v75, v[12:13], off
	v_lshl_add_u64 v[12:13], v[12:13], 0, s[40:41]
	v_cvt_pk_bf16_f32 v16, v42, v42
	s_waitcnt vmcnt(35)
	global_store_short v[14:15], v16, off
	v_lshl_add_u64 v[14:15], v[14:15], 0, s[40:41]
	v_lshlrev_b32_e32 v43, 16, v43
	v_fmac_f32_e32 v43, v10, v42
	global_load_ushort v76, v[12:13], off
	v_lshl_add_u64 v[12:13], v[12:13], 0, s[40:41]
	v_cvt_pk_bf16_f32 v16, v43, v43
	s_waitcnt vmcnt(36)
	global_store_short v[14:15], v16, off
	v_lshl_add_u64 v[14:15], v[14:15], 0, s[40:41]
	v_lshlrev_b32_e32 v44, 16, v44
	v_fmac_f32_e32 v44, v10, v43
	global_load_ushort v77, v[12:13], off
	v_lshl_add_u64 v[12:13], v[12:13], 0, s[40:41]
	v_cvt_pk_bf16_f32 v16, v44, v44
	s_waitcnt vmcnt(37)
	global_store_short v[14:15], v16, off
	v_lshl_add_u64 v[14:15], v[14:15], 0, s[40:41]
	v_lshlrev_b32_e32 v45, 16, v45
	v_fmac_f32_e32 v45, v10, v44
	global_load_ushort v78, v[12:13], off
	v_lshl_add_u64 v[12:13], v[12:13], 0, s[40:41]
	v_cvt_pk_bf16_f32 v16, v45, v45
	s_waitcnt vmcnt(38)
	global_store_short v[14:15], v16, off
	v_lshl_add_u64 v[14:15], v[14:15], 0, s[40:41]
	v_lshlrev_b32_e32 v46, 16, v46
	v_fmac_f32_e32 v46, v10, v45
	global_load_ushort v79, v[12:13], off
	v_lshl_add_u64 v[12:13], v[12:13], 0, s[40:41]
	v_cvt_pk_bf16_f32 v16, v46, v46
	s_waitcnt vmcnt(39)
	global_store_short v[14:15], v16, off
	v_lshl_add_u64 v[14:15], v[14:15], 0, s[40:41]
	v_lshlrev_b32_e32 v47, 16, v47
	v_fmac_f32_e32 v47, v10, v46
	global_load_ushort v80, v[12:13], off
	v_lshl_add_u64 v[12:13], v[12:13], 0, s[40:41]
	v_cvt_pk_bf16_f32 v16, v47, v47
	s_waitcnt vmcnt(40)
	global_store_short v[14:15], v16, off
	v_lshl_add_u64 v[14:15], v[14:15], 0, s[40:41]
	v_lshlrev_b32_e32 v48, 16, v48
	v_fmac_f32_e32 v48, v10, v47
	global_load_ushort v81, v[12:13], off
	v_lshl_add_u64 v[12:13], v[12:13], 0, s[40:41]
	v_cvt_pk_bf16_f32 v16, v48, v48
	s_waitcnt vmcnt(41)
	global_store_short v[14:15], v16, off
	v_lshl_add_u64 v[14:15], v[14:15], 0, s[40:41]
	v_lshlrev_b32_e32 v49, 16, v49
	v_fmac_f32_e32 v49, v10, v48
	global_load_ushort v82, v[12:13], off
	v_lshl_add_u64 v[12:13], v[12:13], 0, s[40:41]
	v_cvt_pk_bf16_f32 v16, v49, v49
	s_waitcnt vmcnt(42)
	global_store_short v[14:15], v16, off
	v_lshl_add_u64 v[14:15], v[14:15], 0, s[40:41]
	v_lshlrev_b32_e32 v50, 16, v50
	v_fmac_f32_e32 v50, v10, v49
	global_load_ushort v83, v[12:13], off
	v_lshl_add_u64 v[12:13], v[12:13], 0, s[40:41]
	v_cvt_pk_bf16_f32 v16, v50, v50
	s_waitcnt vmcnt(43)
	global_store_short v[14:15], v16, off
	v_lshl_add_u64 v[14:15], v[14:15], 0, s[40:41]
	v_lshlrev_b32_e32 v51, 16, v51
	v_fmac_f32_e32 v51, v10, v50
	global_load_ushort v84, v[12:13], off
	v_lshl_add_u64 v[12:13], v[12:13], 0, s[40:41]
	v_cvt_pk_bf16_f32 v16, v51, v51
	s_waitcnt vmcnt(44)
	global_store_short v[14:15], v16, off
	v_lshl_add_u64 v[14:15], v[14:15], 0, s[40:41]
	v_lshlrev_b32_e32 v52, 16, v52
	v_fmac_f32_e32 v52, v10, v51
	global_load_ushort v85, v[12:13], off
	v_lshl_add_u64 v[12:13], v[12:13], 0, s[40:41]
	v_cvt_pk_bf16_f32 v16, v52, v52
	s_waitcnt vmcnt(45)
	global_store_short v[14:15], v16, off
	v_lshl_add_u64 v[14:15], v[14:15], 0, s[40:41]
	v_lshlrev_b32_e32 v53, 16, v53
	v_fmac_f32_e32 v53, v10, v52
	global_load_ushort v86, v[12:13], off
	v_lshl_add_u64 v[12:13], v[12:13], 0, s[40:41]
	v_cvt_pk_bf16_f32 v16, v53, v53
	s_waitcnt vmcnt(46)
	global_store_short v[14:15], v16, off
	v_lshl_add_u64 v[14:15], v[14:15], 0, s[40:41]
	v_lshlrev_b32_e32 v54, 16, v54
	v_fmac_f32_e32 v54, v10, v53
	global_load_ushort v87, v[12:13], off
	v_lshl_add_u64 v[12:13], v[12:13], 0, s[40:41]
	v_cvt_pk_bf16_f32 v16, v54, v54
	s_waitcnt vmcnt(47)
	global_store_short v[14:15], v16, off
	v_lshl_add_u64 v[14:15], v[14:15], 0, s[40:41]
	v_lshlrev_b32_e32 v55, 16, v55
	v_fmac_f32_e32 v55, v10, v54
	global_load_ushort v88, v[12:13], off
	v_lshl_add_u64 v[12:13], v[12:13], 0, s[40:41]
	v_cvt_pk_bf16_f32 v16, v55, v55
	s_waitcnt vmcnt(48)
	global_store_short v[14:15], v16, off
	v_lshl_add_u64 v[14:15], v[14:15], 0, s[40:41]
	v_lshlrev_b32_e32 v56, 16, v56
	v_fmac_f32_e32 v56, v10, v55
	global_load_ushort v89, v[12:13], off
	v_lshl_add_u64 v[12:13], v[12:13], 0, s[40:41]
	v_cvt_pk_bf16_f32 v16, v56, v56
	s_waitcnt vmcnt(49)
	global_store_short v[14:15], v16, off
	v_lshl_add_u64 v[14:15], v[14:15], 0, s[40:41]
	v_lshlrev_b32_e32 v57, 16, v57
	v_fmac_f32_e32 v57, v10, v56
	global_load_ushort v90, v[12:13], off
	v_lshl_add_u64 v[12:13], v[12:13], 0, s[40:41]
	v_cvt_pk_bf16_f32 v16, v57, v57
	s_waitcnt vmcnt(50)
	global_store_short v[14:15], v16, off
	v_lshl_add_u64 v[14:15], v[14:15], 0, s[40:41]
	v_lshlrev_b32_e32 v58, 16, v58
	v_fmac_f32_e32 v58, v10, v57
	global_load_ushort v91, v[12:13], off
	v_lshl_add_u64 v[12:13], v[12:13], 0, s[40:41]
	v_cvt_pk_bf16_f32 v16, v58, v58
	s_waitcnt vmcnt(51)
	global_store_short v[14:15], v16, off
	v_lshl_add_u64 v[14:15], v[14:15], 0, s[40:41]
	v_lshlrev_b32_e32 v59, 16, v59
	v_fmac_f32_e32 v59, v10, v58
	global_load_ushort v92, v[12:13], off
	v_lshl_add_u64 v[12:13], v[12:13], 0, s[40:41]
	v_cvt_pk_bf16_f32 v16, v59, v59
	s_waitcnt vmcnt(52)
	global_store_short v[14:15], v16, off
	v_lshl_add_u64 v[14:15], v[14:15], 0, s[40:41]
	v_lshlrev_b32_e32 v60, 16, v60
	v_fmac_f32_e32 v60, v10, v59
	global_load_ushort v93, v[12:13], off
	v_lshl_add_u64 v[12:13], v[12:13], 0, s[40:41]
	v_cvt_pk_bf16_f32 v16, v60, v60
	s_waitcnt vmcnt(53)
	global_store_short v[14:15], v16, off
	v_lshl_add_u64 v[14:15], v[14:15], 0, s[40:41]
	v_lshlrev_b32_e32 v61, 16, v61
	v_fmac_f32_e32 v61, v10, v60
	global_load_ushort v94, v[12:13], off
	v_lshl_add_u64 v[12:13], v[12:13], 0, s[40:41]
	v_cvt_pk_bf16_f32 v16, v61, v61
	s_waitcnt vmcnt(54)
	global_store_short v[14:15], v16, off
	v_lshl_add_u64 v[14:15], v[14:15], 0, s[40:41]
	v_lshlrev_b32_e32 v62, 16, v62
	v_fmac_f32_e32 v62, v10, v61
	global_load_ushort v95, v[12:13], off
	v_lshl_add_u64 v[12:13], v[12:13], 0, s[40:41]
	v_cvt_pk_bf16_f32 v16, v62, v62
	s_waitcnt vmcnt(55)
	global_store_short v[14:15], v16, off
	v_lshl_add_u64 v[14:15], v[14:15], 0, s[40:41]
	v_lshlrev_b32_e32 v63, 16, v63
	v_fmac_f32_e32 v63, v10, v62
	global_load_ushort v96, v[12:13], off
	v_lshl_add_u64 v[12:13], v[12:13], 0, s[40:41]
	v_cvt_pk_bf16_f32 v16, v63, v63
	s_waitcnt vmcnt(56)
	global_store_short v[14:15], v16, off
	v_lshl_add_u64 v[14:15], v[14:15], 0, s[40:41]
	v_lshlrev_b32_e32 v64, 16, v64
	v_fmac_f32_e32 v64, v10, v63
	global_load_ushort v97, v[12:13], off
	v_lshl_add_u64 v[12:13], v[12:13], 0, s[40:41]
	v_cvt_pk_bf16_f32 v16, v64, v64
	s_waitcnt vmcnt(57)
	global_store_short v[14:15], v16, off
	v_lshl_add_u64 v[14:15], v[14:15], 0, s[40:41]
	v_lshlrev_b32_e32 v65, 16, v65
	v_fmac_f32_e32 v65, v10, v64
	global_load_ushort v98, v[12:13], off
	v_lshl_add_u64 v[12:13], v[12:13], 0, s[40:41]
	v_cvt_pk_bf16_f32 v16, v65, v65
	s_waitcnt vmcnt(58)
	global_store_short v[14:15], v16, off
	v_lshl_add_u64 v[14:15], v[14:15], 0, s[40:41]
	v_lshlrev_b32_e32 v66, 16, v66
	v_fmac_f32_e32 v66, v10, v65
	global_load_ushort v99, v[12:13], off
	v_lshl_add_u64 v[12:13], v[12:13], 0, s[40:41]
	v_cvt_pk_bf16_f32 v16, v66, v66
	s_waitcnt vmcnt(59)
	global_store_short v[14:15], v16, off
	v_lshl_add_u64 v[14:15], v[14:15], 0, s[40:41]
	v_lshlrev_b32_e32 v67, 16, v67
	v_fmac_f32_e32 v67, v10, v66
	global_load_ushort v100, v[12:13], off
	v_lshl_add_u64 v[12:13], v[12:13], 0, s[40:41]
	v_cvt_pk_bf16_f32 v16, v67, v67
	s_waitcnt vmcnt(60)
	global_store_short v[14:15], v16, off
	v_lshl_add_u64 v[14:15], v[14:15], 0, s[40:41]
	v_lshlrev_b32_e32 v68, 16, v68
	v_fmac_f32_e32 v68, v10, v67
	global_load_ushort v101, v[12:13], off
	v_lshl_add_u64 v[12:13], v[12:13], 0, s[40:41]
	v_cvt_pk_bf16_f32 v16, v68, v68
	s_waitcnt vmcnt(61)
	global_store_short v[14:15], v16, off
	v_lshl_add_u64 v[14:15], v[14:15], 0, s[40:41]
	v_lshlrev_b32_e32 v69, 16, v69
	v_fmac_f32_e32 v69, v10, v68
	global_load_ushort v102, v[12:13], off
	v_lshl_add_u64 v[12:13], v[12:13], 0, s[40:41]
	v_cvt_pk_bf16_f32 v16, v69, v69
	s_waitcnt vmcnt(62)
	global_store_short v[14:15], v16, off
	v_lshl_add_u64 v[14:15], v[14:15], 0, s[40:41]
	v_lshlrev_b32_e32 v70, 16, v70
	v_fmac_f32_e32 v70, v10, v69
	global_load_ushort v103, v[12:13], off
	v_lshl_add_u64 v[12:13], v[12:13], 0, s[40:41]
	v_cvt_pk_bf16_f32 v16, v70, v70
	s_waitcnt vmcnt(63)
	global_store_short v[14:15], v16, off
	v_lshl_add_u64 v[14:15], v[14:15], 0, s[40:41]
	v_lshlrev_b32_e32 v71, 16, v71
	v_fmac_f32_e32 v71, v10, v70
	v_cvt_pk_bf16_f32 v16, v71, v71
	s_waitcnt vmcnt(63)
	global_store_short v[14:15], v16, off
	v_lshl_add_u64 v[14:15], v[14:15], 0, s[40:41]
	v_lshlrev_b32_e32 v72, 16, v72
	v_fmac_f32_e32 v72, v10, v71
	v_cvt_pk_bf16_f32 v16, v72, v72
	s_waitcnt vmcnt(62)
	global_store_short v[14:15], v16, off
	v_lshl_add_u64 v[14:15], v[14:15], 0, s[40:41]
	v_lshlrev_b32_e32 v73, 16, v73
	v_fmac_f32_e32 v73, v10, v72
	v_cvt_pk_bf16_f32 v16, v73, v73
	s_waitcnt vmcnt(61)
	global_store_short v[14:15], v16, off
	v_lshl_add_u64 v[14:15], v[14:15], 0, s[40:41]
	v_lshlrev_b32_e32 v74, 16, v74
	v_fmac_f32_e32 v74, v10, v73
	v_cvt_pk_bf16_f32 v16, v74, v74
	s_waitcnt vmcnt(60)
	global_store_short v[14:15], v16, off
	v_lshl_add_u64 v[14:15], v[14:15], 0, s[40:41]
	v_lshlrev_b32_e32 v75, 16, v75
	v_fmac_f32_e32 v75, v10, v74
	v_cvt_pk_bf16_f32 v16, v75, v75
	s_waitcnt vmcnt(59)
	global_store_short v[14:15], v16, off
	v_lshl_add_u64 v[14:15], v[14:15], 0, s[40:41]
	v_lshlrev_b32_e32 v76, 16, v76
	v_fmac_f32_e32 v76, v10, v75
	v_cvt_pk_bf16_f32 v16, v76, v76
	s_waitcnt vmcnt(58)
	global_store_short v[14:15], v16, off
	v_lshl_add_u64 v[14:15], v[14:15], 0, s[40:41]
	v_lshlrev_b32_e32 v77, 16, v77
	v_fmac_f32_e32 v77, v10, v76
	v_cvt_pk_bf16_f32 v16, v77, v77
	s_waitcnt vmcnt(57)
	global_store_short v[14:15], v16, off
	v_lshl_add_u64 v[14:15], v[14:15], 0, s[40:41]
	v_lshlrev_b32_e32 v78, 16, v78
	v_fmac_f32_e32 v78, v10, v77
	v_cvt_pk_bf16_f32 v16, v78, v78
	s_waitcnt vmcnt(56)
	global_store_short v[14:15], v16, off
	v_lshl_add_u64 v[14:15], v[14:15], 0, s[40:41]
	v_lshlrev_b32_e32 v79, 16, v79
	v_fmac_f32_e32 v79, v10, v78
	v_cvt_pk_bf16_f32 v16, v79, v79
	s_waitcnt vmcnt(55)
	global_store_short v[14:15], v16, off
	v_lshl_add_u64 v[14:15], v[14:15], 0, s[40:41]
	v_lshlrev_b32_e32 v80, 16, v80
	v_fmac_f32_e32 v80, v10, v79
	v_cvt_pk_bf16_f32 v16, v80, v80
	s_waitcnt vmcnt(54)
	global_store_short v[14:15], v16, off
	v_lshl_add_u64 v[14:15], v[14:15], 0, s[40:41]
	v_lshlrev_b32_e32 v81, 16, v81
	v_fmac_f32_e32 v81, v10, v80
	v_cvt_pk_bf16_f32 v16, v81, v81
	s_waitcnt vmcnt(53)
	global_store_short v[14:15], v16, off
	v_lshl_add_u64 v[14:15], v[14:15], 0, s[40:41]
	v_lshlrev_b32_e32 v82, 16, v82
	v_fmac_f32_e32 v82, v10, v81
	v_cvt_pk_bf16_f32 v16, v82, v82
	s_waitcnt vmcnt(52)
	global_store_short v[14:15], v16, off
	v_lshl_add_u64 v[14:15], v[14:15], 0, s[40:41]
	v_lshlrev_b32_e32 v83, 16, v83
	v_fmac_f32_e32 v83, v10, v82
	v_cvt_pk_bf16_f32 v16, v83, v83
	s_waitcnt vmcnt(51)
	global_store_short v[14:15], v16, off
	v_lshl_add_u64 v[14:15], v[14:15], 0, s[40:41]
	v_lshlrev_b32_e32 v84, 16, v84
	v_fmac_f32_e32 v84, v10, v83
	v_cvt_pk_bf16_f32 v16, v84, v84
	s_waitcnt vmcnt(50)
	global_store_short v[14:15], v16, off
	v_lshl_add_u64 v[14:15], v[14:15], 0, s[40:41]
	v_lshlrev_b32_e32 v85, 16, v85
	v_fmac_f32_e32 v85, v10, v84
	v_cvt_pk_bf16_f32 v16, v85, v85
	s_waitcnt vmcnt(49)
	global_store_short v[14:15], v16, off
	v_lshl_add_u64 v[14:15], v[14:15], 0, s[40:41]
	v_lshlrev_b32_e32 v86, 16, v86
	v_fmac_f32_e32 v86, v10, v85
	v_cvt_pk_bf16_f32 v16, v86, v86
	s_waitcnt vmcnt(48)
	global_store_short v[14:15], v16, off
	v_lshl_add_u64 v[14:15], v[14:15], 0, s[40:41]
	v_lshlrev_b32_e32 v87, 16, v87
	v_fmac_f32_e32 v87, v10, v86
	v_cvt_pk_bf16_f32 v16, v87, v87
	s_waitcnt vmcnt(47)
	global_store_short v[14:15], v16, off
	v_lshl_add_u64 v[14:15], v[14:15], 0, s[40:41]
	v_lshlrev_b32_e32 v88, 16, v88
	v_fmac_f32_e32 v88, v10, v87
	v_cvt_pk_bf16_f32 v16, v88, v88
	s_waitcnt vmcnt(46)
	global_store_short v[14:15], v16, off
	v_lshl_add_u64 v[14:15], v[14:15], 0, s[40:41]
	v_lshlrev_b32_e32 v89, 16, v89
	v_fmac_f32_e32 v89, v10, v88
	v_cvt_pk_bf16_f32 v16, v89, v89
	s_waitcnt vmcnt(45)
	global_store_short v[14:15], v16, off
	v_lshl_add_u64 v[14:15], v[14:15], 0, s[40:41]
	v_lshlrev_b32_e32 v90, 16, v90
	v_fmac_f32_e32 v90, v10, v89
	v_cvt_pk_bf16_f32 v16, v90, v90
	s_waitcnt vmcnt(44)
	global_store_short v[14:15], v16, off
	v_lshl_add_u64 v[14:15], v[14:15], 0, s[40:41]
	v_lshlrev_b32_e32 v91, 16, v91
	v_fmac_f32_e32 v91, v10, v90
	v_cvt_pk_bf16_f32 v16, v91, v91
	s_waitcnt vmcnt(43)
	global_store_short v[14:15], v16, off
	v_lshl_add_u64 v[14:15], v[14:15], 0, s[40:41]
	v_lshlrev_b32_e32 v92, 16, v92
	v_fmac_f32_e32 v92, v10, v91
	v_cvt_pk_bf16_f32 v16, v92, v92
	s_waitcnt vmcnt(42)
	global_store_short v[14:15], v16, off
	v_lshl_add_u64 v[14:15], v[14:15], 0, s[40:41]
	v_lshlrev_b32_e32 v93, 16, v93
	v_fmac_f32_e32 v93, v10, v92
	v_cvt_pk_bf16_f32 v16, v93, v93
	s_waitcnt vmcnt(41)
	global_store_short v[14:15], v16, off
	v_lshl_add_u64 v[14:15], v[14:15], 0, s[40:41]
	v_lshlrev_b32_e32 v94, 16, v94
	v_fmac_f32_e32 v94, v10, v93
	v_cvt_pk_bf16_f32 v16, v94, v94
	s_waitcnt vmcnt(40)
	global_store_short v[14:15], v16, off
	v_lshl_add_u64 v[14:15], v[14:15], 0, s[40:41]
	v_lshlrev_b32_e32 v95, 16, v95
	v_fmac_f32_e32 v95, v10, v94
	v_cvt_pk_bf16_f32 v16, v95, v95
	s_waitcnt vmcnt(39)
	global_store_short v[14:15], v16, off
	v_lshl_add_u64 v[14:15], v[14:15], 0, s[40:41]
	v_lshlrev_b32_e32 v96, 16, v96
	v_fmac_f32_e32 v96, v10, v95
	v_cvt_pk_bf16_f32 v16, v96, v96
	s_waitcnt vmcnt(38)
	global_store_short v[14:15], v16, off
	v_lshl_add_u64 v[14:15], v[14:15], 0, s[40:41]
	v_lshlrev_b32_e32 v97, 16, v97
	v_fmac_f32_e32 v97, v10, v96
	v_cvt_pk_bf16_f32 v16, v97, v97
	s_waitcnt vmcnt(37)
	global_store_short v[14:15], v16, off
	v_lshl_add_u64 v[14:15], v[14:15], 0, s[40:41]
	v_lshlrev_b32_e32 v98, 16, v98
	v_fmac_f32_e32 v98, v10, v97
	v_cvt_pk_bf16_f32 v16, v98, v98
	s_waitcnt vmcnt(36)
	global_store_short v[14:15], v16, off
	v_lshl_add_u64 v[14:15], v[14:15], 0, s[40:41]
	v_lshlrev_b32_e32 v99, 16, v99
	v_fmac_f32_e32 v99, v10, v98
	v_cvt_pk_bf16_f32 v16, v99, v99
	s_waitcnt vmcnt(35)
	global_store_short v[14:15], v16, off
	v_lshl_add_u64 v[14:15], v[14:15], 0, s[40:41]
	v_lshlrev_b32_e32 v100, 16, v100
	v_fmac_f32_e32 v100, v10, v99
	v_cvt_pk_bf16_f32 v16, v100, v100
	s_waitcnt vmcnt(34)
	global_store_short v[14:15], v16, off
	v_lshl_add_u64 v[14:15], v[14:15], 0, s[40:41]
	v_lshlrev_b32_e32 v101, 16, v101
	v_fmac_f32_e32 v101, v10, v100
	v_cvt_pk_bf16_f32 v16, v101, v101
	s_waitcnt vmcnt(33)
	global_store_short v[14:15], v16, off
	v_lshl_add_u64 v[14:15], v[14:15], 0, s[40:41]
	v_lshlrev_b32_e32 v102, 16, v102
	v_fmac_f32_e32 v102, v10, v101
	v_cvt_pk_bf16_f32 v16, v102, v102
	s_waitcnt vmcnt(32)
	global_store_short v[14:15], v16, off
	v_lshl_add_u64 v[14:15], v[14:15], 0, s[40:41]
	v_lshlrev_b32_e32 v103, 16, v103
	v_fmac_f32_e32 v103, v10, v102
	v_add_u32_e32 v4, s34, v4
	v_cmp_lt_i32_e32 vcc, s35, v4
	s_or_b64 s[20:21], vcc, s[20:21]
	s_andn2_b64 exec, exec, s[20:21]
	s_cbranch_execnz .LBB0_807
